# v16 + attention QK^T K-fragment reads triple-buffered (3 LDS reads in flight instead of 1)
# baseline (speedup 1.0000x reference)
; #define LAS __attribute__((address_space(3)))
; __device__ __forceinline__ void attn_mfma(LAS unsigned char* lds, int layer, int G, const int wave_s) {
;     ...
;             { const LAS unsigned char* Ks = lds + bf * AT_BUF + kv * 16384;
; #pragma unroll
;               for (int d0 = 0; d0 < 8; ++d0) { const int cb = (d0 * 16 + hi * 8) * 2;
;                   const bf16x8 k0f = *(const LAS bf16x8*)(Ks + AT_KSWZ(r32, cb)), k1f = *(const LAS bf16x8*)(Ks + AT_KSWZ(32 + r32, cb));
;                   p0 = __builtin_amdgcn_mfma_f32_32x32x16_bf16(k0f, qr[d0], p0, 0, 0, 0);
;                   p1 = __builtin_amdgcn_mfma_f32_32x32x16_bf16(k1f, qr[d0], p1, 0, 0, 0); } }
;             if (i < nw) { const int kb = AT_KEY0(i) + 4 * hi - (q0 + r32);
; #pragma unroll
;                 for (int r = 0; r < 16; ++r) { const int d = kb + (r & 3) + 8 * (r >> 2), kk = d + q0 + r32;
;                     if (d < -WINDOW || d > WINDOW || kk < 0) p0[r] = -1.0e30f;
;                     if (d + 32 < -WINDOW || d + 32 > WINDOW || kk + 32 > SEQ - 1 || kk + 32 < 0) p1[r] = -1.0e30f;
;                     if (kk > SEQ - 1) p0[r] = -1.0e30f; } }
.LBB0_796:
	s_and_b32 s71, s17, 0x10000
	v_add_u32_e32 v0, s71, v188
	v_add_u32_e32 v199, v0, v200
	v_add_u32_e32 v222, v0, v202
	v_add_u32_e32 v239, v0, v203
	ds_read_b128 v[66:69], v199
	ds_read_b128 v[82:85], v199 offset:8192
	ds_read_b128 v[240:243], v222
	ds_read_b128 v[218:221], v222 offset:8192
	ds_read_b128 v[248:251], v239
	v_add_u32_e32 v244, v0, v204
	v_add_u32_e32 v246, v0, v205
	v_add_u32_e32 v247, v0, v206
	v_add_u32_e32 v252, v0, v207
	v_add_u32_e32 v171, v0, v208
	s_add_i32 s42, s53, -1
	s_cmp_lt_u32 s42, s25
	s_waitcnt lgkmcnt(4)
	v_mfma_f32_32x32x16_bf16 v[66:81], v[66:69], v[98:101], 0
	s_waitcnt lgkmcnt(3)
	v_mfma_f32_32x32x16_bf16 v[82:97], v[82:85], v[98:101], 0
	s_waitcnt lgkmcnt(2)
	v_mfma_f32_32x32x16_bf16 v[66:81], v[240:243], v[102:105], v[66:81]
	ds_read_b128 v[240:243], v239 offset:8192
	s_waitcnt lgkmcnt(2)
	v_mfma_f32_32x32x16_bf16 v[82:97], v[218:221], v[102:105], v[82:97]
	ds_read_b128 v[218:221], v244
	s_waitcnt lgkmcnt(2)
	v_mfma_f32_32x32x16_bf16 v[66:81], v[248:251], v[106:109], v[66:81]
	ds_read_b128 v[248:251], v244 offset:8192
	s_waitcnt lgkmcnt(2)
	v_mfma_f32_32x32x16_bf16 v[82:97], v[240:243], v[106:109], v[82:97]
	ds_read_b128 v[240:243], v246
	s_waitcnt lgkmcnt(2)
	v_mfma_f32_32x32x16_bf16 v[66:81], v[218:221], v[110:113], v[66:81]
	ds_read_b128 v[218:221], v246 offset:8192
	s_waitcnt lgkmcnt(2)
	v_mfma_f32_32x32x16_bf16 v[82:97], v[248:251], v[110:113], v[82:97]
	ds_read_b128 v[248:251], v247
	s_waitcnt lgkmcnt(2)
	v_mfma_f32_32x32x16_bf16 v[66:81], v[240:243], v[114:117], v[66:81]
	ds_read_b128 v[240:243], v247 offset:8192
	s_waitcnt lgkmcnt(2)
	v_mfma_f32_32x32x16_bf16 v[82:97], v[218:221], v[114:117], v[82:97]
	ds_read_b128 v[218:221], v252
	s_waitcnt lgkmcnt(2)
	v_mfma_f32_32x32x16_bf16 v[66:81], v[248:251], v[118:121], v[66:81]
	ds_read_b128 v[248:251], v252 offset:8192
	s_waitcnt lgkmcnt(2)
	v_mfma_f32_32x32x16_bf16 v[82:97], v[240:243], v[118:121], v[82:97]
	ds_read_b128 v[240:243], v171
	s_waitcnt lgkmcnt(2)
	v_mfma_f32_32x32x16_bf16 v[66:81], v[218:221], v[122:125], v[66:81]
	ds_read_b128 v[218:221], v171 offset:8192
	s_waitcnt lgkmcnt(2)
	v_mfma_f32_32x32x16_bf16 v[82:97], v[248:251], v[122:125], v[82:97]
	s_waitcnt lgkmcnt(1)
	v_mfma_f32_32x32x16_bf16 v[66:81], v[240:243], v[126:129], v[66:81]
	s_waitcnt lgkmcnt(0)
	v_mfma_f32_32x32x16_bf16 v[82:97], v[218:221], v[126:129], v[82:97]
	s_cbranch_scc0 .LBB0_798
	v_add_u32_e32 v0, s68, v215
	v_add_u32_e32 v218, s68, v214
	v_add_u32_e32 v199, 0xffffff80, v0
	v_add_co_u32_e32 v219, vcc, 0xfffffeff, v218
	v_cmp_gt_i32_e64 s[42:43], 0, v199
	v_add_u32_e32 v219, 0xffffff1f, v218
	s_or_b64 s[54:55], vcc, s[42:43]
	v_cmp_gt_u32_e32 vcc, s5, v219
	v_add_u32_e32 v219, 0xffffefa0, v0
	v_cmp_gt_u32_e64 s[42:43], s9, v219
	s_or_b64 vcc, vcc, s[42:43]
	v_cndmask_b32_e32 v82, v82, v238, vcc
	v_cmp_lt_i32_e32 vcc, s8, v199
	s_or_b64 vcc, vcc, s[54:55]
	v_add_u32_e32 v199, 0xffffff81, v0
	v_add_u32_e32 v219, 0xffffff00, v218
	v_cndmask_b32_e32 v66, v66, v238, vcc
	v_cmp_gt_u32_e32 vcc, s5, v219
	v_cmp_gt_i32_e64 s[42:43], 0, v199
	v_add_u32_e32 v219, 0xffffff20, v218
	s_or_b64 s[54:55], vcc, s[42:43]
	v_cmp_gt_u32_e32 vcc, s5, v219
	v_add_u32_e32 v219, 0xffffefa1, v0
	v_cmp_gt_u32_e64 s[42:43], s9, v219
	s_or_b64 vcc, vcc, s[42:43]
	v_cndmask_b32_e32 v83, v83, v238, vcc
	v_cmp_lt_i32_e32 vcc, s8, v199
	s_or_b64 vcc, vcc, s[54:55]
	v_add_u32_e32 v199, 0xffffff82, v0
	v_add_u32_e32 v219, 0xffffff01, v218
	v_cndmask_b32_e32 v67, v67, v238, vcc
	v_cmp_gt_u32_e32 vcc, s5, v219
	v_cmp_gt_i32_e64 s[42:43], 0, v199
	v_add_u32_e32 v219, 0xffffff21, v218
	s_or_b64 s[54:55], vcc, s[42:43]
	v_cmp_gt_u32_e32 vcc, s5, v219
	v_add_u32_e32 v219, 0xffffefa2, v0
	v_cmp_gt_u32_e64 s[42:43], s9, v219
	s_or_b64 vcc, vcc, s[42:43]
	v_cndmask_b32_e32 v84, v84, v238, vcc
	v_cmp_lt_i32_e32 vcc, s8, v199
	s_or_b64 vcc, vcc, s[54:55]
	v_add_u32_e32 v199, 0xffffff83, v0
	v_add_u32_e32 v219, 0xffffff02, v218
	v_cndmask_b32_e32 v68, v68, v238, vcc
	v_cmp_gt_u32_e32 vcc, s5, v219
	v_cmp_gt_i32_e64 s[42:43], 0, v199
	v_add_u32_e32 v219, 0xffffff22, v218
	s_or_b64 s[54:55], vcc, s[42:43]
	v_cmp_gt_u32_e32 vcc, s5, v219
	v_add_u32_e32 v219, 0xffffefa3, v0
	v_cmp_gt_u32_e64 s[42:43], s9, v219
	s_or_b64 vcc, vcc, s[42:43]
	v_cndmask_b32_e32 v85, v85, v238, vcc
	v_cmp_lt_i32_e32 vcc, s8, v199
	s_or_b64 vcc, vcc, s[54:55]
	v_add_u32_e32 v199, 0xffffff88, v0
	v_add_u32_e32 v219, 0xffffff07, v218
	v_cndmask_b32_e32 v69, v69, v238, vcc
	v_cmp_gt_u32_e32 vcc, s5, v219
	v_cmp_gt_i32_e64 s[42:43], 0, v199
	v_add_u32_e32 v219, 0xffffff27, v218
	s_or_b64 s[54:55], vcc, s[42:43]
	v_cmp_gt_u32_e32 vcc, s5, v219
	v_add_u32_e32 v219, 0xffffefa8, v0
	v_cmp_gt_u32_e64 s[42:43], s9, v219
	s_or_b64 vcc, vcc, s[42:43]
	v_cndmask_b32_e32 v86, v86, v238, vcc
	v_cmp_lt_i32_e32 vcc, s8, v199
	s_or_b64 vcc, vcc, s[54:55]
	v_add_u32_e32 v199, 0xffffff89, v0
	v_add_u32_e32 v219, 0xffffff08, v218
	v_cndmask_b32_e32 v70, v70, v238, vcc
	v_cmp_gt_u32_e32 vcc, s5, v219
	v_cmp_gt_i32_e64 s[42:43], 0, v199
	v_add_u32_e32 v219, 0xffffff28, v218
	s_or_b64 s[54:55], vcc, s[42:43]
	v_cmp_gt_u32_e32 vcc, s5, v219
; __device__ __forceinline__ void attn_mfma(LAS unsigned char* lds, int layer, int G, const int wave_s) {
;     ...
;             if (i < nw) { const int kb = AT_KEY0(i) + 4 * hi - (q0 + r32);
; #pragma unroll
;                 for (int r = 0; r < 16; ++r) { const int d = kb + (r & 3) + 8 * (r >> 2), kk = d + q0 + r32;
;                     if (d < -WINDOW || d > WINDOW || kk < 0) p0[r] = -1.0e30f;
;                     if (d + 32 < -WINDOW || d + 32 > WINDOW || kk + 32 > SEQ - 1 || kk + 32 < 0) p1[r] = -1.0e30f;
;                     if (kk > SEQ - 1) p0[r] = -1.0e30f; } }
	v_add_u32_e32 v219, 0xffffefa9, v0
	v_cmp_gt_u32_e64 s[42:43], s9, v219
	s_or_b64 vcc, vcc, s[42:43]
	v_cndmask_b32_e32 v87, v87, v238, vcc
	v_cmp_lt_i32_e32 vcc, s8, v199
	s_or_b64 vcc, vcc, s[54:55]
	v_add_u32_e32 v199, 0xffffff8a, v0
	v_add_u32_e32 v219, 0xffffff09, v218
	v_cndmask_b32_e32 v71, v71, v238, vcc
	v_cmp_gt_u32_e32 vcc, s5, v219
	v_cmp_gt_i32_e64 s[42:43], 0, v199
	v_add_u32_e32 v219, 0xffffff29, v218
	s_or_b64 s[54:55], vcc, s[42:43]
	v_cmp_gt_u32_e32 vcc, s5, v219
	v_add_u32_e32 v219, 0xffffefaa, v0
	v_cmp_gt_u32_e64 s[42:43], s9, v219
	s_or_b64 vcc, vcc, s[42:43]
	v_cndmask_b32_e32 v88, v88, v238, vcc
	v_cmp_lt_i32_e32 vcc, s8, v199
	s_or_b64 vcc, vcc, s[54:55]
	v_add_u32_e32 v199, 0xffffff8b, v0
	v_add_u32_e32 v219, 0xffffff0a, v218
	v_cndmask_b32_e32 v72, v72, v238, vcc
	v_cmp_gt_u32_e32 vcc, s5, v219
	v_cmp_gt_i32_e64 s[42:43], 0, v199
	v_add_u32_e32 v219, 0xffffff2a, v218
	s_or_b64 s[54:55], vcc, s[42:43]
	v_cmp_gt_u32_e32 vcc, s5, v219
	v_add_u32_e32 v219, 0xffffefab, v0
	v_cmp_gt_u32_e64 s[42:43], s9, v219
	s_or_b64 vcc, vcc, s[42:43]
	v_cndmask_b32_e32 v89, v89, v238, vcc
	v_cmp_lt_i32_e32 vcc, s8, v199
	s_or_b64 vcc, vcc, s[54:55]
	v_add_u32_e32 v199, 0xffffff90, v0
	v_add_u32_e32 v219, 0xffffff0f, v218
	v_cndmask_b32_e32 v73, v73, v238, vcc
	v_cmp_gt_u32_e32 vcc, s5, v219
	v_cmp_gt_i32_e64 s[42:43], 0, v199
	v_add_u32_e32 v219, 0xffffff2f, v218
	s_or_b64 s[54:55], vcc, s[42:43]
	v_cmp_gt_u32_e32 vcc, s5, v219
	v_add_u32_e32 v219, 0xffffefb0, v0
	v_cmp_gt_u32_e64 s[42:43], s9, v219
	s_or_b64 vcc, vcc, s[42:43]
	v_cndmask_b32_e32 v90, v90, v238, vcc
	v_cmp_lt_i32_e32 vcc, s8, v199
	s_or_b64 vcc, vcc, s[54:55]
	v_add_u32_e32 v199, 0xffffff91, v0
	v_add_u32_e32 v219, 0xffffff10, v218
	v_cndmask_b32_e32 v74, v74, v238, vcc
	v_cmp_gt_u32_e32 vcc, s5, v219
	v_cmp_gt_i32_e64 s[42:43], 0, v199
	v_add_u32_e32 v219, 0xffffff30, v218
	s_or_b64 s[54:55], vcc, s[42:43]
	v_cmp_gt_u32_e32 vcc, s5, v219
	v_add_u32_e32 v219, 0xffffefb1, v0
	v_cmp_gt_u32_e64 s[42:43], s9, v219
	s_or_b64 vcc, vcc, s[42:43]
	v_cndmask_b32_e32 v91, v91, v238, vcc
	v_cmp_lt_i32_e32 vcc, s8, v199
	s_or_b64 vcc, vcc, s[54:55]
	v_add_u32_e32 v199, 0xffffff92, v0
	v_add_u32_e32 v219, 0xffffff11, v218
	v_cndmask_b32_e32 v75, v75, v238, vcc
	v_cmp_gt_u32_e32 vcc, s5, v219
	v_cmp_gt_i32_e64 s[42:43], 0, v199
	v_add_u32_e32 v219, 0xffffff31, v218
	s_or_b64 s[54:55], vcc, s[42:43]
	v_cmp_gt_u32_e32 vcc, s5, v219
	v_add_u32_e32 v219, 0xffffefb2, v0
	v_cmp_gt_u32_e64 s[42:43], s9, v219
	s_or_b64 vcc, vcc, s[42:43]
	v_cndmask_b32_e32 v92, v92, v238, vcc
	v_cmp_lt_i32_e32 vcc, s8, v199
	s_or_b64 vcc, vcc, s[54:55]
	v_add_u32_e32 v199, 0xffffff93, v0
	v_add_u32_e32 v219, 0xffffff12, v218
	v_cndmask_b32_e32 v76, v76, v238, vcc
	v_cmp_gt_u32_e32 vcc, s5, v219
	v_cmp_gt_i32_e64 s[42:43], 0, v199
	v_add_u32_e32 v219, 0xffffff32, v218
	s_or_b64 s[54:55], vcc, s[42:43]
	v_cmp_gt_u32_e32 vcc, s5, v219
	v_add_u32_e32 v219, 0xffffefb3, v0
	v_cmp_gt_u32_e64 s[42:43], s9, v219
	s_or_b64 vcc, vcc, s[42:43]
	v_cndmask_b32_e32 v93, v93, v238, vcc
	v_cmp_lt_i32_e32 vcc, s8, v199
	s_or_b64 vcc, vcc, s[54:55]
	v_add_u32_e32 v199, 0xffffff98, v0
	v_add_u32_e32 v219, 0xffffff17, v218
	v_cndmask_b32_e32 v77, v77, v238, vcc
	v_cmp_gt_u32_e32 vcc, s5, v219
	v_cmp_gt_i32_e64 s[42:43], 0, v199
	v_add_u32_e32 v219, 0xffffff37, v218
	s_or_b64 s[54:55], vcc, s[42:43]
	v_cmp_gt_u32_e32 vcc, s5, v219
	v_add_u32_e32 v219, 0xffffefb8, v0
	v_cmp_gt_u32_e64 s[42:43], s9, v219
	s_or_b64 vcc, vcc, s[42:43]
	v_cndmask_b32_e32 v94, v94, v238, vcc
	v_cmp_lt_i32_e32 vcc, s8, v199
	s_or_b64 vcc, vcc, s[54:55]
	v_add_u32_e32 v199, 0xffffff99, v0
	v_add_u32_e32 v219, 0xffffff18, v218
	v_cndmask_b32_e32 v78, v78, v238, vcc
	v_cmp_gt_u32_e32 vcc, s5, v219
	v_cmp_gt_i32_e64 s[42:43], 0, v199
	v_add_u32_e32 v219, 0xffffff38, v218
	s_or_b64 s[54:55], vcc, s[42:43]
	v_cmp_gt_u32_e32 vcc, s5, v219
	v_add_u32_e32 v219, 0xffffefb9, v0
	v_cmp_gt_u32_e64 s[42:43], s9, v219
	s_or_b64 vcc, vcc, s[42:43]
	v_cndmask_b32_e32 v95, v95, v238, vcc
	v_cmp_lt_i32_e32 vcc, s8, v199
	s_or_b64 vcc, vcc, s[54:55]
	v_add_u32_e32 v199, 0xffffff9a, v0
	v_add_u32_e32 v219, 0xffffff19, v218
	v_cndmask_b32_e32 v79, v79, v238, vcc
	v_cmp_gt_u32_e32 vcc, s5, v219
	v_cmp_gt_i32_e64 s[42:43], 0, v199
	v_add_u32_e32 v219, 0xffffff39, v218
	s_or_b64 s[54:55], vcc, s[42:43]
	v_cmp_gt_u32_e32 vcc, s5, v219
	v_add_u32_e32 v219, 0xffffefba, v0
	v_cmp_gt_u32_e64 s[42:43], s9, v219
	s_or_b64 vcc, vcc, s[42:43]
	v_cndmask_b32_e32 v96, v96, v238, vcc
	v_cmp_lt_i32_e32 vcc, s8, v199
	s_or_b64 vcc, vcc, s[54:55]
	v_add_u32_e32 v199, 0xffffff9b, v0
	v_add_u32_e32 v219, 0xffffff1a, v218
	v_cndmask_b32_e32 v80, v80, v238, vcc
	v_cmp_gt_u32_e32 vcc, s5, v219
	v_cmp_gt_i32_e64 s[42:43], 0, v199
	v_add_u32_e32 v218, 0xffffff3a, v218
	v_add_u32_e32 v0, 0xffffefbb, v0
	s_or_b64 s[54:55], vcc, s[42:43]
	v_cmp_gt_u32_e32 vcc, s5, v218
	v_cmp_gt_u32_e64 s[42:43], s9, v0
	s_or_b64 vcc, vcc, s[42:43]
	v_cndmask_b32_e32 v97, v97, v238, vcc
	v_cmp_lt_i32_e32 vcc, s8, v199
	s_or_b64 vcc, vcc, s[54:55]
	s_nop 0
	v_cndmask_b32_e32 v81, v81, v238, vcc
